# attention loop re-sequenced into matrix-only and vector-only segments, the two 4-wave halves run one segment apart (ping-pong); V-tile LDS writes moved to the head of the matrix segments
# speedup vs baseline: 1.0093x; 1.0064x over previous
; #define SBAR() __builtin_amdgcn_sched_barrier(0)
; #define VMW() asm volatile("s_waitcnt vmcnt(0)" ::: "memory")
; #define SLOAD_H(Kp, Vp, k0) do { S.st_v0 = load8(ROW(Vp, k0, sr)); S.st_v1 = load8(ROW(Vp, k0, 32 + sr));              \
;                          S.st_k0 = load8(ROW(Kp, k0, sr)); S.st_k1 = load8(ROW(Kp, k0, 32 + sr)); } while (0)
; #define SWRITE_HV(bf) do { *(bf16x8*)(V_lds + (bf) * SHM_V + vst0) = S.st_v0; *(bf16x8*)(V_lds + (bf) * SHM_V + vst1) = S.st_v1; } while (0)
; #define SWRITE_H(bf) do { SWRITE_HV(bf); SWRITE_HK(bf); } while (0)
; #define MASKT(P0_, P1_) sel_mask_tile(P0_, P1_, mw.x, mw.y, hi)
; template <int KB>
; __device__ __forceinline__ void qkt(f32x16& p0, f32x16& p1, const char* K_lds, int r32, int hi, const bf16x8* qr) {
;     p0 = f32x16{}; p1 = f32x16{};
;     const char* kb[4];
; #pragma unroll
;     for (int dd = 0; dd < 4; ++dd) kb[dd] = K_lds + KB * SHM_K + KSWZ(r32, (dd * 16 + hi * 8) * 2);
; #pragma unroll
;     for (int d0 = 0; d0 < 8; ++d0) { const char* a = kb[d0 & 3] + (d0 >> 2) * 128;
;         bf16x8 b0 = *reinterpret_cast<const bf16x8*>(a);
;         bf16x8 b1 = *reinterpret_cast<const bf16x8*>(a + 32 * 256);
;         p0 = __builtin_amdgcn_mfma_f32_32x32x16_bf16(b0, qr[d0], p0, 0, 0, 0);
;         p1 = __builtin_amdgcn_mfma_f32_32x32x16_bf16(b1, qr[d0], p1, 0, 0, 0); }
; }
; __device__ __forceinline__ void attn_block(const BlockRef& cur, const BlockRef& nxt, char* lds, Seam& S) {
;     ...
;     SWRITE_HV(0); SBAR();
;     mw = LDMASK(0);
;     if (NT > 1) { SLOAD_H(Kh, Vh, KBASE(1)); }
;     SBAR(); qkt<0>(pA0, pA1, K_lds, r32, hi, S.qr);
;     MASKT(pA0, pA1); partialSM(pA0, pA1, m_reg, mnA, alA);
;     if (NT > 1) { VMW(); SWRITE_H(1); }
;     __syncthreads();
.LBB0_1298:
	v_readfirstlane_b32 s83, v0
	s_lshr_b32 s12, s38, 6
	s_or_b32 s81, s12, 3
	s_and_b32 s12, s83, 0x3fffffc0
	s_lshl_b32 s12, s12, 2
	s_add_i32 s84, s12, 0
	s_lshr_b32 s12, s83, 1
	s_and_b32 s12, s12, 0x7fffffe0
	v_and_b32_e32 v88, 31, v0
	v_or_b32_e32 v186, s12, v88
	s_mov_b32 s82, 1
	v_lshlrev_b32_e32 v165, 9, v186
	s_add_i32 s84, s84, 0x10000
	s_waitcnt vmcnt(1)
	ds_write_b128 v197, v[130:133]
	s_waitcnt vmcnt(0)
	ds_write_b128 v198, v[134:137]
	v_mov_b32_e32 v183, v167
	v_lshl_add_u64 v[2:3], s[70:71], 0, v[182:183]
	v_mov_b32_e32 v177, v167
	v_mov_b32_e32 v185, v167
	v_lshl_add_u64 v[2:3], v[2:3], 0, v[176:177]
	v_lshl_add_u64 v[4:5], s[70:71], 0, v[184:185]
	global_load_dwordx2 v[86:87], v165, s[68:69]
	v_lshl_add_u64 v[4:5], v[4:5], 0, v[176:177]
	global_load_dwordx4 v[50:53], v[2:3], off
	global_load_dwordx4 v[54:57], v[4:5], off
	v_lshl_add_u64 v[2:3], s[6:7], 0, v[182:183]
	v_lshl_add_u64 v[2:3], v[2:3], 0, v[176:177]
	v_lshl_add_u64 v[4:5], s[6:7], 0, v[184:185]
	v_lshl_add_u64 v[4:5], v[4:5], 0, v[176:177]
	global_load_dwordx4 v[58:61], v[2:3], off
	global_load_dwordx4 v[62:65], v[4:5], off
	ds_read_b128 v[2:5], v199 offset:32768
	ds_read_b128 v[6:9], v199 offset:32896
	s_mov_b32 s36, s13
	s_mov_b32 s37, s13
	s_mov_b32 s38, s13
	s_waitcnt lgkmcnt(1)
	v_mfma_f32_32x32x16_bf16 v[34:49], v[2:5], v[126:129], 0
	ds_read_b128 v[2:5], v199 offset:40960
	ds_read_b128 v[10:13], v199 offset:41088
	s_mov_b32 s39, s13
	s_mov_b32 s40, s13
	s_mov_b32 s41, s13
	s_mov_b32 s42, s13
	s_mov_b32 s43, s13
	s_mov_b32 s44, s13
	s_waitcnt lgkmcnt(1)
	v_mfma_f32_32x32x16_bf16 v[18:33], v[2:5], v[126:129], 0
	ds_read_b128 v[2:5], v200 offset:32768
	ds_read_b128 v[14:17], v200 offset:32896
	s_mov_b32 s45, s13
	s_mov_b32 s46, s13
	s_mov_b32 s47, s13
	s_mov_b32 s48, s13
	s_mov_b32 s49, s13
	s_mov_b32 s50, s13
	s_waitcnt lgkmcnt(1)
	v_mfma_f32_32x32x16_bf16 v[34:49], v[2:5], v[122:125], v[34:49]
	ds_read_b128 v[2:5], v200 offset:40960
	ds_read_b128 v[66:69], v200 offset:41088
	s_mov_b32 s51, s13
	v_lshl_add_u32 v185, v88, 2, s84
	v_lshl_add_u32 v183, v163, 2, s84
	v_add_u32_e32 v188, v170, v252
	s_mov_b64 s[16:17], s[70:71]
	s_mov_b64 s[100:101], s[6:7]
	v_mov_b32_e32 v205, 0
	s_waitcnt lgkmcnt(1)
	v_mfma_f32_32x32x16_bf16 v[18:33], v[2:5], v[122:125], v[18:33]
	ds_read_b128 v[2:5], v201 offset:32768
	ds_read_b128 v[70:73], v201 offset:32896
	s_waitcnt lgkmcnt(1)
	v_mfma_f32_32x32x16_bf16 v[34:49], v[2:5], v[118:121], v[34:49]
	ds_read_b128 v[2:5], v201 offset:40960
	ds_read_b128 v[74:77], v201 offset:41088
	s_waitcnt lgkmcnt(1)
	v_mfma_f32_32x32x16_bf16 v[18:33], v[2:5], v[118:121], v[18:33]
	ds_read_b128 v[2:5], v202 offset:32768
	ds_read_b128 v[78:81], v202 offset:32896
	s_waitcnt lgkmcnt(1)
	v_mfma_f32_32x32x16_bf16 v[34:49], v[2:5], v[114:117], v[34:49]
	ds_read_b128 v[2:5], v202 offset:40960
	ds_read_b128 v[82:85], v202 offset:41088
	s_waitcnt vmcnt(0)
	s_waitcnt vmcnt(3)
	ds_write_b128 v197, v[50:53] offset:16384
	s_waitcnt vmcnt(2)
	ds_write_b128 v198, v[54:57] offset:16384
	s_waitcnt vmcnt(1)
	ds_write_b128 v204, v[58:61] offset:49152
	s_waitcnt vmcnt(0)
	ds_write_b128 v204, v[62:65] offset:57344
	s_waitcnt lgkmcnt(0)
	s_barrier
	v_mfma_f32_32x32x16_bf16 v[34:49], v[6:9], v[110:113], v[34:49]
	v_mfma_f32_32x32x16_bf16 v[18:33], v[2:5], v[114:117], v[18:33]
	v_mfma_f32_32x32x16_bf16 v[34:49], v[14:17], v[106:109], v[34:49]
	v_mfma_f32_32x32x16_bf16 v[18:33], v[10:13], v[110:113], v[18:33]
	v_mov_b64_e32 v[2:3], s[36:37]
	v_mov_b64_e32 v[4:5], s[38:39]
	v_mov_b64_e32 v[6:7], s[40:41]
	v_mov_b64_e32 v[8:9], s[42:43]
	v_mov_b64_e32 v[10:11], s[44:45]
	v_mov_b64_e32 v[12:13], s[46:47]
	v_mov_b64_e32 v[14:15], s[48:49]
	v_mfma_f32_32x32x16_bf16 v[34:49], v[70:73], v[102:105], v[34:49]
	v_mov_b64_e32 v[16:17], s[50:51]
	v_mov_b64_e32 v[64:65], v[16:17]
	v_mov_b64_e32 v[62:63], v[14:15]
	v_mov_b64_e32 v[60:61], v[12:13]
	v_mov_b64_e32 v[58:59], v[10:11]
	v_mov_b64_e32 v[56:57], v[8:9]
	v_mov_b64_e32 v[54:55], v[6:7]
	v_mfma_f32_32x32x16_bf16 v[18:33], v[66:69], v[106:109], v[18:33]
	v_lshrrev_b32_e32 v66, v163, v86
	v_bfe_i32 v68, v66, 0, 1
	v_lshrrev_b32_e32 v67, v163, v87
	v_bfe_i32 v69, v67, 0, 1
	v_bfe_i32 v70, v67, 2, 1
	v_bfe_i32 v71, v67, 3, 1
	v_bfe_i32 v72, v67, 8, 1
	v_mfma_f32_32x32x16_bf16 v[34:49], v[78:81], v[98:101], v[34:49]
	v_bfe_i32 v73, v67, 9, 1
	v_bfe_i32 v78, v67, 18, 1
	v_bfe_i32 v79, v67, 19, 1
	v_bfe_i32 v80, v67, 24, 1
	v_bfe_i32 v81, v67, 25, 1
	v_mov_b64_e32 v[52:53], v[4:5]
	v_mov_b64_e32 v[50:51], v[2:3]
	v_mfma_f32_32x32x16_bf16 v[18:33], v[74:77], v[102:105], v[18:33]
	s_nop 3
	v_bitop3_b32 v68, v34, s74, v68 bitop3:0xe4
	v_bfe_i32 v34, v66, 1, 1
	v_bitop3_b32 v35, v35, s74, v34 bitop3:0xe4
	v_bfe_i32 v34, v66, 2, 1
	v_bitop3_b32 v36, v36, s74, v34 bitop3:0xe4
	v_bfe_i32 v34, v66, 3, 1
	v_bitop3_b32 v37, v37, s74, v34 bitop3:0xe4
	v_bfe_i32 v34, v66, 8, 1
	v_bitop3_b32 v38, v38, s74, v34 bitop3:0xe4
	v_bfe_i32 v34, v66, 9, 1
	v_bitop3_b32 v39, v39, s74, v34 bitop3:0xe4
	v_bfe_i32 v34, v66, 10, 1
	v_bitop3_b32 v40, v40, s74, v34 bitop3:0xe4
	v_bfe_i32 v34, v66, 11, 1
	v_mfma_f32_32x32x16_bf16 v[18:33], v[82:85], v[98:101], v[18:33]
	v_bitop3_b32 v41, v41, s74, v34 bitop3:0xe4
	v_bfe_i32 v34, v66, 16, 1
	v_bitop3_b32 v42, v42, s74, v34 bitop3:0xe4
	v_bfe_i32 v34, v66, 17, 1
	v_bitop3_b32 v43, v43, s74, v34 bitop3:0xe4
	v_bfe_i32 v34, v66, 18, 1
	v_bitop3_b32 v44, v44, s74, v34 bitop3:0xe4
	v_bfe_i32 v34, v66, 19, 1
	v_bitop3_b32 v45, v45, s74, v34 bitop3:0xe4
	v_bfe_i32 v34, v66, 24, 1
	v_bitop3_b32 v46, v46, s74, v34 bitop3:0xe4
	v_bfe_i32 v34, v66, 25, 1
	v_bitop3_b32 v47, v47, s74, v34 bitop3:0xe4
; __device__ __forceinline__ void sel_mask_tile(f32x16& p0, f32x16& p1, unsigned wlo, unsigned whi, int hi) {
;     const unsigned NEGB = 0xff800000u;
;     const unsigned lo = wlo >> (4 * hi), h2 = whi >> (4 * hi);
; #pragma unroll
;     for (int r = 0; r < 16; ++r) {
;         const int c = (r & 3) + 8 * (r >> 2);
;         const unsigned m0 = (unsigned)__builtin_amdgcn_sbfe((int)lo, c, 1), m1 = (unsigned)__builtin_amdgcn_sbfe((int)h2, c, 1);
;         p0[r] = __uint_as_float((__float_as_uint(p0[r]) & m0) | (NEGB & ~m0));
;         p1[r] = __uint_as_float((__float_as_uint(p1[r]) & m1) | (NEGB & ~m1));
;     }
; }
; __device__ __forceinline__ void partialSM(f32x16& p0, f32x16& p1, float& m_reg, float& mn, float& alpha) {
;     float pmax = p0[0];
; #pragma unroll
;     for (int r = 1; r < 16; ++r) pmax = fmaxf(pmax, p0[r]);
; #pragma unroll
;     for (int r = 0; r < 16; ++r) pmax = fmaxf(pmax, p1[r]);
;     { auto rr = __builtin_amdgcn_permlane32_swap(__float_as_uint(pmax), __float_as_uint(pmax), false, false);
;       pmax = fmaxf(__uint_as_float(rr[0]), __uint_as_float(rr[1])); }
;     constexpr float C2 = 1.4426950408889634f * SCALE;
;     if (__builtin_expect(__all((pmax - m_reg) * SCALE <= THR), 1)) { mn = m_reg; alpha = 1.f; }
;     else { mn = fmaxf(m_reg, pmax); alpha = __builtin_amdgcn_exp2f((m_reg - mn) * C2); m_reg = mn; }
;     const float mnL = -mn * C2;
; #pragma unroll
;     for (int r = 0; r < 16; ++r) p0[r] = fmaf(p0[r], C2, mnL);
; #pragma unroll
;     for (int r = 0; r < 16; ++r) p1[r] = fmaf(p1[r], C2, mnL);
; #pragma unroll
;     for (int r = 0; r < 16; ++r) p0[r] = __builtin_amdgcn_exp2f(p0[r]);
; }
	v_bfe_i32 v34, v66, 26, 1
	v_bitop3_b32 v48, v48, s74, v34 bitop3:0xe4
	v_bfe_i32 v34, v66, 27, 1
	v_bitop3_b32 v18, v18, s74, v69 bitop3:0xe4
	v_bfe_i32 v69, v67, 1, 1
	v_bfe_i32 v74, v67, 10, 1
	v_bfe_i32 v75, v67, 11, 1
	v_bfe_i32 v76, v67, 16, 1
	v_bfe_i32 v77, v67, 17, 1
	v_bfe_i32 v82, v67, 26, 1
	v_bfe_i32 v66, v67, 27, 1
	v_bitop3_b32 v49, v49, s74, v34 bitop3:0xe4
	v_max_f32_e32 v34, v35, v35
	v_max_f32_e32 v67, v68, v68
	v_max_f32_e32 v34, v67, v34
	v_max3_f32 v34, v34, v36, v37
	v_max3_f32 v34, v34, v38, v39
	v_max3_f32 v34, v34, v40, v41
	v_max3_f32 v34, v34, v42, v43
	v_max3_f32 v34, v34, v44, v45
	v_max3_f32 v34, v34, v46, v47
	v_max3_f32 v34, v34, v48, v49
	v_bitop3_b32 v19, v19, s74, v69 bitop3:0xe4
	v_bitop3_b32 v20, v20, s74, v70 bitop3:0xe4
	v_max3_f32 v34, v34, v18, v19
	v_bitop3_b32 v21, v21, s74, v71 bitop3:0xe4
	v_bitop3_b32 v22, v22, s74, v72 bitop3:0xe4
	v_max3_f32 v34, v34, v20, v21
	v_bitop3_b32 v23, v23, s74, v73 bitop3:0xe4
	v_bitop3_b32 v24, v24, s74, v74 bitop3:0xe4
	v_max3_f32 v34, v34, v22, v23
	v_bitop3_b32 v25, v25, s74, v75 bitop3:0xe4
	v_bitop3_b32 v26, v26, s74, v76 bitop3:0xe4
	v_max3_f32 v34, v34, v24, v25
	v_bitop3_b32 v27, v27, s74, v77 bitop3:0xe4
	v_bitop3_b32 v28, v28, s74, v78 bitop3:0xe4
	v_max3_f32 v34, v34, v26, v27
	v_bitop3_b32 v29, v29, s74, v79 bitop3:0xe4
	v_bitop3_b32 v30, v30, s74, v80 bitop3:0xe4
	v_max3_f32 v34, v34, v28, v29
	v_bitop3_b32 v31, v31, s74, v81 bitop3:0xe4
	v_bitop3_b32 v32, v32, s74, v82 bitop3:0xe4
	v_max3_f32 v34, v34, v30, v31
	v_bitop3_b32 v33, v33, s74, v66 bitop3:0xe4
	v_max3_f32 v34, v34, v32, v33
	v_mov_b32_e32 v66, v34
	s_nop 1
	v_permlane32_swap_b32_e32 v34, v66
	v_max_f32_e32 v66, v66, v66
	v_max_f32_e32 v34, v34, v34
	v_max_f32_e32 v34, v34, v66
	v_add_f32_e32 v66, 0x7149f2ca, v34
	v_mul_f32_e32 v66, 0x3db504f3, v66
	v_max_f32_e32 v34, 0xf149f2ca, v34
	v_cmp_ge_f32_e32 vcc, s75, v66
	v_sub_f32_e32 v66, 0xf149f2ca, v34
	v_mul_f32_e32 v66, 0x3e0293ee, v66
	s_cmp_eq_u64 vcc, exec
	v_exp_f32_e32 v66, v66
	s_cselect_b64 vcc, -1, 0
	v_cndmask_b32_e32 v206, v34, v203, vcc
	v_mul_f32_e32 v34, 0xbe0293ee, v206
	v_mov_b32_e32 v67, v34
	v_cndmask_b32_e64 v177, v66, 1.0, vcc
	v_fmamk_f32 v66, v68, 0x3e0293ee, v34
	v_fmamk_f32 v35, v35, 0x3e0293ee, v34
	v_fmamk_f32 v36, v36, 0x3e0293ee, v34
	v_fmamk_f32 v37, v37, 0x3e0293ee, v34
	v_fmamk_f32 v38, v38, 0x3e0293ee, v34
	v_fmamk_f32 v39, v39, 0x3e0293ee, v34
	v_fmamk_f32 v40, v40, 0x3e0293ee, v34
	v_fmamk_f32 v41, v41, 0x3e0293ee, v34
	v_fmamk_f32 v42, v42, 0x3e0293ee, v34
	v_fmamk_f32 v43, v43, 0x3e0293ee, v34
	v_fmamk_f32 v44, v44, 0x3e0293ee, v34
	v_fmamk_f32 v45, v45, 0x3e0293ee, v34
	v_fmamk_f32 v46, v46, 0x3e0293ee, v34
	v_fmamk_f32 v47, v47, 0x3e0293ee, v34
	v_fmamk_f32 v48, v48, 0x3e0293ee, v34
	v_fmac_f32_e32 v67, 0x3e0293ee, v49
	v_exp_f32_e32 v219, v66
	v_exp_f32_e32 v220, v35
	v_exp_f32_e32 v221, v36
	v_exp_f32_e32 v222, v37
	v_exp_f32_e32 v223, v38
	v_exp_f32_e32 v225, v39
	v_exp_f32_e32 v224, v40
	v_exp_f32_e32 v226, v41
	v_exp_f32_e32 v211, v42
	v_exp_f32_e32 v212, v43
	v_exp_f32_e32 v213, v44
	v_exp_f32_e32 v215, v45
	v_exp_f32_e32 v214, v46
	v_exp_f32_e32 v216, v47
	v_exp_f32_e32 v217, v48
	v_exp_f32_e32 v218, v67
	s_lshl_b32 s36, s83, 8
	v_pk_fma_f32 v[152:153], v[32:33], s[14:15], v[34:35] op_sel_hi:[1,0,0]
	v_pk_fma_f32 v[156:157], v[30:31], s[14:15], v[34:35] op_sel_hi:[1,0,0]
	v_pk_fma_f32 v[160:161], v[28:29], s[14:15], v[34:35] op_sel_hi:[1,0,0]
	v_pk_fma_f32 v[150:151], v[26:27], s[14:15], v[34:35] op_sel_hi:[1,0,0]
	v_pk_fma_f32 v[154:155], v[24:25], s[14:15], v[34:35] op_sel_hi:[1,0,0]
	v_pk_fma_f32 v[158:159], v[22:23], s[14:15], v[34:35] op_sel_hi:[1,0,0]
	v_pk_fma_f32 v[192:193], v[20:21], s[14:15], v[34:35] op_sel_hi:[1,0,0]
	v_pk_fma_f32 v[194:195], v[18:19], s[14:15], v[34:35] op_sel_hi:[1,0,0]
	s_and_b32 s36, s36, 0xffffc000
	v_mov_b64_e32 v[48:49], v[16:17]
	v_mov_b64_e32 v[32:33], v[16:17]
	v_or_b32_e32 v179, s36, v254
	v_mov_b64_e32 v[46:47], v[14:15]
	v_mov_b64_e32 v[44:45], v[12:13]
	v_mov_b64_e32 v[42:43], v[10:11]
	v_mov_b64_e32 v[40:41], v[8:9]
	v_mov_b64_e32 v[38:39], v[6:7]
	v_mov_b64_e32 v[36:37], v[4:5]
	v_mov_b64_e32 v[34:35], v[2:3]
	v_mov_b64_e32 v[30:31], v[14:15]
	v_mov_b64_e32 v[28:29], v[12:13]
	v_mov_b64_e32 v[26:27], v[10:11]
	v_mov_b64_e32 v[24:25], v[8:9]
	v_mov_b64_e32 v[22:23], v[6:7]
	v_mov_b64_e32 v[20:21], v[4:5]
	v_mov_b64_e32 v[18:19], v[2:3]
	s_mov_b32 s76, 0
	v_readfirstlane_b32 s77, v0
	s_nop 3
	s_lshr_b32 s77, s77, 8
	s_cmp_eq_u32 s77, 0
	s_cbranch_scc1 .Lp5_lead
	s_barrier
; __device__ __forceinline__ void finishSM(f32x16& p0, f32x16& p1, float alpha, float& l_reg, bf16x8& pa0, bf16x8& pa1, bf16x8& pa2, bf16x8& pa3) {
; #pragma unroll
;     for (int r = 0; r < 16; ++r) p1[r] = __builtin_amdgcn_exp2f(p1[r]);
;     float ps = 0;
; #pragma unroll
;     for (int r = 0; r < 16; ++r) ps += p0[r];
; #pragma unroll
;     for (int r = 0; r < 16; ++r) ps += p1[r];
;     { auto rr = __builtin_amdgcn_permlane32_swap(__float_as_uint(ps), __float_as_uint(ps), false, false);
;       ps = __uint_as_float(rr[0]) + __uint_as_float(rr[1]); }
;     l_reg = l_reg * alpha + ps;
;     ...
;     PK4(p0, 0, pa0); PK4(p0, 8, pa1); PK4(p1, 0, pa2); PK4(p1, 8, pa3);
.Lp5_lead:
.LBB0_1299:
	v_exp_f32_e32 v209, v150
	v_add_f32_e32 v150, v220, v219
	v_add_f32_e32 v150, v221, v150
	v_add_f32_e32 v150, v222, v150
	v_add_f32_e32 v150, v223, v150
	v_add_f32_e32 v150, v225, v150
	v_add_f32_e32 v150, v224, v150
	v_add_f32_e32 v150, v226, v150
	v_add_f32_e32 v150, v211, v150
	v_add_f32_e32 v150, v212, v150
	v_exp_f32_e32 v194, v194
	v_exp_f32_e32 v195, v195
	v_exp_f32_e32 v192, v192
	v_exp_f32_e32 v193, v193
	v_exp_f32_e32 v158, v158
	v_exp_f32_e32 v159, v159
	v_exp_f32_e32 v207, v154
	v_exp_f32_e32 v208, v155
	v_exp_f32_e32 v210, v151
	v_exp_f32_e32 v160, v160
	v_exp_f32_e32 v161, v161
	v_exp_f32_e32 v227, v156
	v_cvt_pk_bf16_f32 v151, v224, v226
	v_cvt_pk_bf16_f32 v154, v214, v216
	v_cvt_pk_bf16_f32 v155, v217, v218
	v_cvt_pk_bf16_f32 v156, v194, v195
	v_exp_f32_e32 v228, v157
	v_exp_f32_e32 v229, v152
	v_exp_f32_e32 v230, v153
	v_cvt_pk_bf16_f32 v152, v211, v212
	v_cvt_pk_bf16_f32 v153, v213, v215
	v_cvt_pk_bf16_f32 v157, v192, v193
	v_cvt_pk_bf16_f32 v211, v229, v230
	v_add_f32_e32 v249, v213, v150
	v_add_f32_e32 v249, v215, v249
	v_add_f32_e32 v249, v214, v249
	v_add_f32_e32 v249, v216, v249
	v_add_f32_e32 v249, v217, v249
	v_add_f32_e32 v249, v218, v249
	v_add_f32_e32 v249, v194, v249
	v_add_f32_e32 v248, v195, v249
	v_add_f32_e32 v248, v192, v248
	v_add_f32_e32 v248, v193, v248
	v_add_f32_e32 v248, v158, v248
	v_add_f32_e32 v248, v159, v248
	v_add_f32_e32 v248, v207, v248
	v_add_f32_e32 v248, v208, v248
	v_add_f32_e32 v248, v209, v248
	v_add_f32_e32 v248, v210, v248
	v_add_f32_e32 v248, v160, v248
	v_add_f32_e32 v248, v161, v248
	v_add_f32_e32 v248, v227, v248
	v_add_f32_e32 v248, v228, v248
	v_add_f32_e32 v248, v229, v248
	v_add_f32_e32 v181, v230, v248
	v_cvt_pk_bf16_f32 v148, v219, v220
	v_cvt_pk_bf16_f32 v149, v221, v222
	v_cvt_pk_bf16_f32 v150, v223, v225
	v_cvt_pk_bf16_f32 v158, v158, v159
	v_cvt_pk_bf16_f32 v159, v207, v208
	v_cvt_pk_bf16_f32 v208, v209, v210
	v_cvt_pk_bf16_f32 v210, v227, v228
	v_cvt_pk_bf16_f32 v209, v160, v161
	s_waitcnt lgkmcnt(0)
	s_barrier
	s_cmp_eq_u32 s76, 0
	s_cbranch_scc1 .Lp5_vw_a
	s_waitcnt vmcnt(0)
	ds_write_b128 v197, v[130:133] offset:16384
	ds_write_b128 v198, v[134:137] offset:16384
.Lp5_vw_a:
	global_load_dwordx2 v[146:147], v179, s[68:69] offset:-8
	s_add_u32 s98, s16, 0x40000
	s_addc_u32 s99, s17, 0
	global_load_dwordx4 v[130:133], v188, s[98:99]
	s_add_u32 s98, s16, 0x50000
	s_addc_u32 s99, s17, 0
	global_load_dwordx4 v[134:137], v188, s[98:99]
	s_add_u32 s98, s100, 0x40000
	s_addc_u32 s99, s101, 0
	global_load_dwordx4 v[138:141], v188, s[98:99]
	s_add_u32 s98, s100, 0x50000
	s_addc_u32 s99, s101, 0
	global_load_dwordx4 v[142:145], v188, s[98:99]
	ds_read_b128 v[66:69], v199 offset:49152
	ds_read_b128 v[82:85], v199 offset:57344
	ds_read_b128 v[172:175], v200 offset:49152
	ds_read_b128 v[232:235], v200 offset:57344
	ds_read_b128 v[236:239], v201 offset:49152
	ds_read_b128 v[240:243], v201 offset:57344
	ds_read_b128 v[244:247], v202 offset:49152
	s_waitcnt lgkmcnt(6)
	v_mfma_f32_32x32x16_bf16 v[66:81], v[66:69], v[126:129], 0
	s_waitcnt lgkmcnt(5)
	v_mfma_f32_32x32x16_bf16 v[82:97], v[82:85], v[126:129], 0
	s_waitcnt lgkmcnt(4)
	v_mfma_f32_32x32x16_bf16 v[66:81], v[172:175], v[122:125], v[66:81]
	ds_read_b128 v[172:175], v202 offset:57344
	s_waitcnt lgkmcnt(4)
	v_mfma_f32_32x32x16_bf16 v[82:97], v[232:235], v[122:125], v[82:97]
	ds_read_b128 v[232:235], v199 offset:49280
	s_waitcnt lgkmcnt(4)
	v_mfma_f32_32x32x16_bf16 v[66:81], v[236:239], v[118:121], v[66:81]
	ds_read_b128 v[236:239], v199 offset:57472
	s_waitcnt lgkmcnt(4)
	v_mfma_f32_32x32x16_bf16 v[82:97], v[240:243], v[118:121], v[82:97]
	ds_read_b128 v[240:243], v200 offset:49280
	s_waitcnt lgkmcnt(4)
	v_mfma_f32_32x32x16_bf16 v[66:81], v[244:247], v[114:117], v[66:81]
	ds_read_b128 v[244:247], v200 offset:57472
	s_waitcnt lgkmcnt(4)
	v_mfma_f32_32x32x16_bf16 v[82:97], v[172:175], v[114:117], v[82:97]
	ds_read_b128 v[172:175], v201 offset:49280
	s_waitcnt lgkmcnt(4)
	v_mfma_f32_32x32x16_bf16 v[66:81], v[232:235], v[110:113], v[66:81]
	ds_read_b128 v[232:235], v201 offset:57472
	s_waitcnt lgkmcnt(4)
	v_mfma_f32_32x32x16_bf16 v[82:97], v[236:239], v[110:113], v[82:97]
	ds_read_b128 v[236:239], v202 offset:49280
	s_waitcnt lgkmcnt(4)
	v_mfma_f32_32x32x16_bf16 v[66:81], v[240:243], v[106:109], v[66:81]
	ds_read_b128 v[240:243], v202 offset:57472
	s_waitcnt lgkmcnt(4)
	v_mfma_f32_32x32x16_bf16 v[82:97], v[244:247], v[106:109], v[82:97]
	s_waitcnt lgkmcnt(3)
	v_mfma_f32_32x32x16_bf16 v[66:81], v[172:175], v[102:105], v[66:81]
	s_waitcnt lgkmcnt(2)
	v_mfma_f32_32x32x16_bf16 v[82:97], v[232:235], v[102:105], v[82:97]
	s_waitcnt lgkmcnt(1)
	v_mfma_f32_32x32x16_bf16 v[66:81], v[236:239], v[98:101], v[66:81]
	s_waitcnt lgkmcnt(0)
	v_mfma_f32_32x32x16_bf16 v[82:97], v[240:243], v[98:101], v[82:97]
	ds_read_b64_tr_b16 v[172:173], v1 offset:0x0
	ds_read_b64_tr_b16 v[174:175], v1 offset:0x800
	ds_read_b64_tr_b16 v[212:213], v1 offset:0x200
	ds_read_b64_tr_b16 v[214:215], v1 offset:0xa00
	ds_read_b64_tr_b16 v[216:217], v1 offset:0x400
	ds_read_b64_tr_b16 v[218:219], v1 offset:0xc00
	ds_read_b64_tr_b16 v[220:221], v1 offset:0x600
	ds_read_b64_tr_b16 v[222:223], v1 offset:0xe00
	ds_read_b64_tr_b16 v[224:225], v1 offset:0x1000
	ds_read_b64_tr_b16 v[226:227], v1 offset:0x1800
	ds_read_b64_tr_b16 v[232:233], v1 offset:0x1200
	ds_read_b64_tr_b16 v[234:235], v1 offset:0x1a00
	ds_read_b64_tr_b16 v[236:237], v1 offset:0x1400
	ds_read_b64_tr_b16 v[238:239], v1 offset:0x1c00
	s_waitcnt lgkmcnt(12)
	v_mfma_f32_32x32x16_bf16 v[2:17], v[148:151], v[172:175], v[2:17]
	ds_read_b64_tr_b16 v[240:241], v1 offset:0x1600
	ds_read_b64_tr_b16 v[242:243], v1 offset:0x1e00
	s_waitcnt lgkmcnt(12)
; __device__ __forceinline__ void sel_mask_tile(f32x16& p0, f32x16& p1, unsigned wlo, unsigned whi, int hi) {
;     const unsigned NEGB = 0xff800000u;
;     const unsigned lo = wlo >> (4 * hi), h2 = whi >> (4 * hi);
; #pragma unroll
;     for (int r = 0; r < 16; ++r) {
;         const int c = (r & 3) + 8 * (r >> 2);
;         const unsigned m0 = (unsigned)__builtin_amdgcn_sbfe((int)lo, c, 1), m1 = (unsigned)__builtin_amdgcn_sbfe((int)h2, c, 1);
;         p0[r] = __uint_as_float((__float_as_uint(p0[r]) & m0) | (NEGB & ~m0));
;         p1[r] = __uint_as_float((__float_as_uint(p1[r]) & m1) | (NEGB & ~m1));
;     }
; }
; __device__ __forceinline__ void partialSM(f32x16& p0, f32x16& p1, float& m_reg, float& mn, float& alpha) {
;     float pmax = p0[0];
; #pragma unroll
;     for (int r = 1; r < 16; ++r) pmax = fmaxf(pmax, p0[r]);
; #pragma unroll
;     for (int r = 0; r < 16; ++r) pmax = fmaxf(pmax, p1[r]);
;     { auto rr = __builtin_amdgcn_permlane32_swap(__float_as_uint(pmax), __float_as_uint(pmax), false, false);
;       pmax = fmaxf(__uint_as_float(rr[0]), __uint_as_float(rr[1])); }
;     constexpr float C2 = 1.4426950408889634f * SCALE;
;     if (__builtin_expect(__all((pmax - m_reg) * SCALE <= THR), 1)) { mn = m_reg; alpha = 1.f; }
;     else { mn = fmaxf(m_reg, pmax); alpha = __builtin_amdgcn_exp2f((m_reg - mn) * C2); m_reg = mn; }
; template <int VB>
; __device__ __forceinline__ void pv_tile(f32x16* o, int vb0, bf16x8 pa0, bf16x8 pa1, bf16x8 pa2, bf16x8 pa3) {
;     ...
;     PV_D0(0); PV_D0(1); PV_D0(2); PV_D0(3);
	v_mfma_f32_32x32x16_bf16 v[50:65], v[148:151], v[212:215], v[50:65]
	ds_read_b64_tr_b16 v[244:245], v1 offset:0x2000
	ds_read_b64_tr_b16 v[246:247], v1 offset:0x2800
	s_waitcnt lgkmcnt(12)
	v_mfma_f32_32x32x16_bf16 v[34:49], v[148:151], v[216:219], v[34:49]
	ds_read_b64_tr_b16 v[248:249], v1 offset:0x2200
	ds_read_b64_tr_b16 v[250:251], v1 offset:0x2a00
	s_waitcnt lgkmcnt(12)
	v_mfma_f32_32x32x16_bf16 v[18:33], v[148:151], v[220:223], v[18:33]
	ds_read_b64_tr_b16 v[220:221], v1 offset:0x2400
	ds_read_b64_tr_b16 v[222:223], v1 offset:0x2c00
	s_waitcnt lgkmcnt(12)
	v_mfma_f32_32x32x16_bf16 v[2:17], v[152:155], v[224:227], v[2:17]
	ds_read_b64_tr_b16 v[224:225], v1 offset:0x2600
	ds_read_b64_tr_b16 v[226:227], v1 offset:0x2e00
	s_waitcnt lgkmcnt(12)
	v_mfma_f32_32x32x16_bf16 v[50:65], v[152:155], v[232:235], v[50:65]
	ds_read_b64_tr_b16 v[232:233], v1 offset:0x3000
	ds_read_b64_tr_b16 v[234:235], v1 offset:0x3800
	s_waitcnt lgkmcnt(12)
	v_mfma_f32_32x32x16_bf16 v[34:49], v[152:155], v[236:239], v[34:49]
	ds_read_b64_tr_b16 v[236:237], v1 offset:0x3200
	ds_read_b64_tr_b16 v[238:239], v1 offset:0x3a00
	s_waitcnt lgkmcnt(12)
	v_mfma_f32_32x32x16_bf16 v[18:33], v[152:155], v[240:243], v[18:33]
	ds_read_b64_tr_b16 v[240:241], v1 offset:0x3400
	ds_read_b64_tr_b16 v[242:243], v1 offset:0x3c00
	s_waitcnt lgkmcnt(12)
	v_mfma_f32_32x32x16_bf16 v[2:17], v[156:159], v[244:247], v[2:17]
	ds_read_b64_tr_b16 v[244:245], v1 offset:0x3600
	ds_read_b64_tr_b16 v[246:247], v1 offset:0x3e00
	s_waitcnt lgkmcnt(12)
	v_mfma_f32_32x32x16_bf16 v[50:65], v[156:159], v[248:251], v[50:65]
	s_waitcnt lgkmcnt(10)
	v_mfma_f32_32x32x16_bf16 v[34:49], v[156:159], v[220:223], v[34:49]
	s_waitcnt lgkmcnt(8)
	v_mfma_f32_32x32x16_bf16 v[18:33], v[156:159], v[224:227], v[18:33]
	s_waitcnt lgkmcnt(6)
	v_mfma_f32_32x32x16_bf16 v[2:17], v[208:211], v[232:235], v[2:17]
	s_waitcnt lgkmcnt(4)
	v_mfma_f32_32x32x16_bf16 v[50:65], v[208:211], v[236:239], v[50:65]
	s_waitcnt lgkmcnt(2)
	v_mfma_f32_32x32x16_bf16 v[34:49], v[208:211], v[240:243], v[34:49]
	s_waitcnt lgkmcnt(0)
	v_mfma_f32_32x32x16_bf16 v[18:33], v[208:211], v[244:247], v[18:33]
	s_waitcnt vmcnt(0)
	ds_write_b128 v204, v[138:141] offset:32768
	ds_write_b128 v204, v[142:145] offset:40960
	s_waitcnt lgkmcnt(0)
	s_barrier
	s_nop 0
	s_waitcnt vmcnt(4)
	v_lshrrev_b32_e32 v160, v163, v146
	v_lshrrev_b32_e32 v161, v163, v147
	v_bfe_i32 v146, v160, 0, 1
	v_bfe_i32 v147, v161, 0, 1
	v_bitop3_b32 v146, v66, s74, v146 bitop3:0xe4
	v_bitop3_b32 v66, v82, s74, v147 bitop3:0xe4
	v_bfe_i32 v82, v160, 1, 1
	v_bfe_i32 v147, v161, 1, 1
	v_bitop3_b32 v82, v67, s74, v82 bitop3:0xe4
	v_bitop3_b32 v67, v83, s74, v147 bitop3:0xe4
	v_bfe_i32 v83, v160, 2, 1
	v_bfe_i32 v147, v161, 2, 1
	v_bitop3_b32 v83, v68, s74, v83 bitop3:0xe4
	v_bitop3_b32 v68, v84, s74, v147 bitop3:0xe4
	v_bfe_i32 v84, v160, 3, 1
	v_bfe_i32 v148, v161, 3, 1
	v_bitop3_b32 v147, v69, s74, v84 bitop3:0xe4
	v_bfe_i32 v84, v160, 8, 1
	v_bitop3_b32 v69, v85, s74, v148 bitop3:0xe4
	v_bfe_i32 v85, v161, 8, 1
	v_bitop3_b32 v148, v70, s74, v84 bitop3:0xe4
	v_bfe_i32 v84, v160, 9, 1
	v_bitop3_b32 v70, v86, s74, v85 bitop3:0xe4
	v_bfe_i32 v85, v161, 9, 1
	v_bitop3_b32 v149, v71, s74, v84 bitop3:0xe4
	v_bfe_i32 v84, v160, 10, 1
	v_bitop3_b32 v71, v87, s74, v85 bitop3:0xe4
	v_bfe_i32 v85, v161, 10, 1
	v_bitop3_b32 v87, v72, s74, v84 bitop3:0xe4
	v_bfe_i32 v84, v160, 11, 1
	v_bitop3_b32 v72, v88, s74, v85 bitop3:0xe4
	v_bfe_i32 v85, v161, 11, 1
	v_bitop3_b32 v88, v73, s74, v84 bitop3:0xe4
	v_bfe_i32 v73, v160, 16, 1
	v_bitop3_b32 v84, v89, s74, v85 bitop3:0xe4
	v_bfe_i32 v85, v161, 16, 1
	v_bitop3_b32 v89, v74, s74, v73 bitop3:0xe4
	v_bfe_i32 v73, v160, 17, 1
	v_bfe_i32 v74, v161, 17, 1
	v_bitop3_b32 v85, v90, s74, v85 bitop3:0xe4
	v_bitop3_b32 v90, v75, s74, v73 bitop3:0xe4
	v_bitop3_b32 v86, v91, s74, v74 bitop3:0xe4
	v_bfe_i32 v73, v160, 18, 1
	v_bfe_i32 v74, v161, 18, 1
	v_bitop3_b32 v91, v76, s74, v73 bitop3:0xe4
	v_bitop3_b32 v76, v92, s74, v74 bitop3:0xe4
	v_bfe_i32 v73, v160, 19, 1
	v_bfe_i32 v74, v161, 19, 1
	v_bitop3_b32 v92, v77, s74, v73 bitop3:0xe4
	v_bitop3_b32 v77, v93, s74, v74 bitop3:0xe4
	v_bfe_i32 v73, v160, 24, 1
	v_bfe_i32 v74, v161, 24, 1
	v_bitop3_b32 v93, v78, s74, v73 bitop3:0xe4
	v_bitop3_b32 v78, v94, s74, v74 bitop3:0xe4
	v_bfe_i32 v73, v160, 25, 1
	v_bfe_i32 v74, v161, 25, 1
	v_bitop3_b32 v79, v79, s74, v73 bitop3:0xe4
	v_bitop3_b32 v73, v95, s74, v74 bitop3:0xe4
	v_bfe_i32 v74, v160, 26, 1
	v_bfe_i32 v75, v161, 26, 1
	v_bitop3_b32 v80, v80, s74, v74 bitop3:0xe4
	v_bitop3_b32 v74, v96, s74, v75 bitop3:0xe4
	v_bfe_i32 v75, v160, 27, 1
	v_bfe_i32 v94, v161, 27, 1
	v_bitop3_b32 v81, v81, s74, v75 bitop3:0xe4
	v_bitop3_b32 v75, v97, s74, v94 bitop3:0xe4
	v_max_f32_e32 v94, v146, v82
	v_max3_f32 v94, v94, v83, v147
	v_max3_f32 v94, v94, v148, v149
	v_max3_f32 v94, v94, v87, v88
	v_max3_f32 v94, v94, v89, v90
	v_max3_f32 v94, v94, v91, v92
	v_max3_f32 v94, v94, v93, v79
	v_max3_f32 v94, v94, v80, v81
	v_max3_f32 v94, v94, v66, v67
	v_max3_f32 v94, v94, v68, v69
	v_max3_f32 v94, v94, v70, v71
	v_max3_f32 v94, v94, v72, v84
	v_max3_f32 v94, v94, v85, v86
	v_max3_f32 v94, v94, v76, v77
	v_max3_f32 v94, v94, v78, v73
	v_max3_f32 v94, v94, v74, v75
	v_mov_b32_e32 v95, v94
	s_nop 1
	v_permlane32_swap_b32_e32 v94, v95
	v_max_f32_e32 v94, v94, v95
	v_sub_f32_e32 v95, v94, v206
	v_mul_f32_e32 v95, 0x3db504f3, v95
	v_cmp_ge_f32_e32 vcc, s75, v95
	s_cmp_eq_u64 vcc, exec
	s_cselect_b64 s[6:7], -1, 0
	s_cbranch_scc1 .Lp5_b1fast
	v_max_f32_e32 v94, v206, v94
	v_sub_f32_e32 v96, v206, v94
	v_mul_f32_e32 v96, 0x3e0293ee, v96
	v_exp_f32_e32 v96, v96
; __device__ __forceinline__ void partialSM(f32x16& p0, f32x16& p1, float& m_reg, float& mn, float& alpha) {
;     ...
;     else { mn = fmaxf(m_reg, pmax); alpha = __builtin_amdgcn_exp2f((m_reg - mn) * C2); m_reg = mn; }
;     const float mnL = -mn * C2;
; #pragma unroll
;     for (int r = 0; r < 16; ++r) p0[r] = fmaf(p0[r], C2, mnL);
; #pragma unroll
;     for (int r = 0; r < 16; ++r) p1[r] = fmaf(p1[r], C2, mnL);
; #pragma unroll
;     for (int r = 0; r < 16; ++r) p0[r] = __builtin_amdgcn_exp2f(p0[r]);
; }
; __device__ __forceinline__ void finishSM(f32x16& p0, f32x16& p1, float alpha, float& l_reg, bf16x8& pa0, bf16x8& pa1, bf16x8& pa2, bf16x8& pa3) {
; #pragma unroll
;     for (int r = 0; r < 16; ++r) p1[r] = __builtin_amdgcn_exp2f(p1[r]);
;     float ps = 0;
; #pragma unroll
;     for (int r = 0; r < 16; ++r) ps += p0[r];
; #pragma unroll
;     for (int r = 0; r < 16; ++r) ps += p1[r];
;     { auto rr = __builtin_amdgcn_permlane32_swap(__float_as_uint(ps), __float_as_uint(ps), false, false);
;       ps = __uint_as_float(rr[0]) + __uint_as_float(rr[1]); }
;     l_reg = l_reg * alpha + ps;
;     ...
;     PK4(p0, 0, pa0); PK4(p0, 8, pa1); PK4(p1, 0, pa2); PK4(p1, 8, pa3);
.Lp5_b1fast:
	s_waitcnt vmcnt(0)
	v_cndmask_b32_e64 v208, v96, 1.0, s[6:7]
	s_not_b64 vcc, s[6:7]
	s_cbranch_vccz .LBB0_1303
	s_and_saveexec_b64 s[36:37], s[0:1]
	ds_write_b32 v185, v208 offset:128
	s_or_b64 exec, exec, s[36:37]
	s_waitcnt lgkmcnt(0)
	ds_read_b128 v[150:153], v183 offset:224
	ds_read_b128 v[154:157], v183 offset:192
	ds_read_b128 v[158:161], v183 offset:160
	ds_read_b128 v[172:175], v183 offset:128
	s_waitcnt lgkmcnt(3)
	v_pk_mul_f32 v[16:17], v[16:17], v[152:153]
	s_waitcnt lgkmcnt(2)
	v_pk_mul_f32 v[12:13], v[12:13], v[156:157]
	s_waitcnt lgkmcnt(1)
	v_pk_mul_f32 v[8:9], v[8:9], v[160:161]
	s_waitcnt lgkmcnt(0)
	v_pk_mul_f32 v[4:5], v[4:5], v[174:175]
	v_pk_mul_f32 v[14:15], v[14:15], v[150:151]
	v_pk_mul_f32 v[10:11], v[10:11], v[154:155]
	v_pk_mul_f32 v[6:7], v[6:7], v[158:159]
	v_pk_mul_f32 v[2:3], v[2:3], v[172:173]
	v_pk_mul_f32 v[64:65], v[64:65], v[152:153]
	v_pk_mul_f32 v[60:61], v[60:61], v[156:157]
	v_pk_mul_f32 v[56:57], v[56:57], v[160:161]
	v_pk_mul_f32 v[52:53], v[52:53], v[174:175]
	v_pk_mul_f32 v[62:63], v[62:63], v[150:151]
	v_pk_mul_f32 v[58:59], v[58:59], v[154:155]
	v_pk_mul_f32 v[54:55], v[54:55], v[158:159]
	v_pk_mul_f32 v[50:51], v[50:51], v[172:173]
	v_pk_mul_f32 v[48:49], v[48:49], v[152:153]
	v_pk_mul_f32 v[44:45], v[44:45], v[156:157]
	v_pk_mul_f32 v[40:41], v[40:41], v[160:161]
	v_pk_mul_f32 v[36:37], v[36:37], v[174:175]
	v_pk_mul_f32 v[46:47], v[46:47], v[150:151]
	v_pk_mul_f32 v[42:43], v[42:43], v[154:155]
	v_pk_mul_f32 v[38:39], v[38:39], v[158:159]
	v_pk_mul_f32 v[34:35], v[34:35], v[172:173]
	v_pk_mul_f32 v[32:33], v[32:33], v[152:153]
	v_pk_mul_f32 v[28:29], v[28:29], v[156:157]
	v_pk_mul_f32 v[24:25], v[24:25], v[160:161]
	v_pk_mul_f32 v[20:21], v[20:21], v[174:175]
	v_pk_mul_f32 v[30:31], v[30:31], v[150:151]
	v_pk_mul_f32 v[26:27], v[26:27], v[154:155]
	v_pk_mul_f32 v[22:23], v[22:23], v[158:159]
	v_pk_mul_f32 v[18:19], v[18:19], v[172:173]
.LBB0_1303:
	v_cndmask_b32_e64 v206, v94, v206, s[6:7]
	v_mul_f32_e32 v207, 0xbe0293ee, v206
	v_fmamk_f32 v94, v146, 0x3e0293ee, v207
	v_fmamk_f32 v82, v82, 0x3e0293ee, v207
	v_fmamk_f32 v83, v83, 0x3e0293ee, v207
	v_fmamk_f32 v95, v147, 0x3e0293ee, v207
	v_fmamk_f32 v96, v148, 0x3e0293ee, v207
	v_fmamk_f32 v97, v149, 0x3e0293ee, v207
	v_fmamk_f32 v87, v87, 0x3e0293ee, v207
	v_fmamk_f32 v88, v88, 0x3e0293ee, v207
	v_fmamk_f32 v89, v89, 0x3e0293ee, v207
	v_fmamk_f32 v90, v90, 0x3e0293ee, v207
	v_fmamk_f32 v91, v91, 0x3e0293ee, v207
	v_fmamk_f32 v92, v92, 0x3e0293ee, v207
	v_fmamk_f32 v93, v93, 0x3e0293ee, v207
	v_fmamk_f32 v79, v79, 0x3e0293ee, v207
	v_fmamk_f32 v80, v80, 0x3e0293ee, v207
	v_fmamk_f32 v81, v81, 0x3e0293ee, v207
	v_exp_f32_e32 v146, v94
	v_exp_f32_e32 v147, v82
	v_exp_f32_e32 v148, v83
	v_exp_f32_e32 v159, v95
	v_exp_f32_e32 v160, v96
	v_exp_f32_e32 v161, v97
	v_exp_f32_e32 v149, v87
	v_exp_f32_e32 v158, v88
	v_exp_f32_e32 v150, v89
	v_exp_f32_e32 v151, v90
	v_exp_f32_e32 v155, v91
	v_exp_f32_e32 v157, v92
	v_exp_f32_e32 v152, v93
	v_exp_f32_e32 v153, v79
	v_exp_f32_e32 v154, v80
	v_exp_f32_e32 v156, v81
	v_fmamk_f32 v210, v71, 0x3e0293ee, v207
	v_fmamk_f32 v209, v78, 0x3e0293ee, v207
	v_fmamk_f32 v217, v66, 0x3e0293ee, v207
	v_fmamk_f32 v218, v67, 0x3e0293ee, v207
	v_fmamk_f32 v219, v68, 0x3e0293ee, v207
	v_fmamk_f32 v220, v69, 0x3e0293ee, v207
	v_fmamk_f32 v221, v70, 0x3e0293ee, v207
	v_fmamk_f32 v211, v72, 0x3e0293ee, v207
	v_fmamk_f32 v212, v84, 0x3e0293ee, v207
	v_fmamk_f32 v213, v85, 0x3e0293ee, v207
	v_fmamk_f32 v214, v86, 0x3e0293ee, v207
	v_fmamk_f32 v215, v76, 0x3e0293ee, v207
	v_fmamk_f32 v216, v77, 0x3e0293ee, v207
	v_fmamk_f32 v222, v73, 0x3e0293ee, v207
	v_fmamk_f32 v223, v74, 0x3e0293ee, v207
	v_fmac_f32_e32 v207, 0x3e0293ee, v75
	v_exp_f32_e32 v211, v211
	v_exp_f32_e32 v212, v212
	v_exp_f32_e32 v213, v213
	v_exp_f32_e32 v214, v214
	v_exp_f32_e32 v215, v215
	v_exp_f32_e32 v216, v216
	v_exp_f32_e32 v207, v207
	v_exp_f32_e32 v250, v219
	v_exp_f32_e32 v219, v209
	v_add_f32_e32 v209, v147, v146
	v_add_f32_e32 v209, v148, v209
	v_add_f32_e32 v209, v159, v209
	v_add_f32_e32 v209, v160, v209
	v_add_f32_e32 v209, v161, v209
	v_add_f32_e32 v209, v149, v209
	v_add_f32_e32 v209, v158, v209
	v_add_f32_e32 v209, v150, v209
	v_add_f32_e32 v209, v151, v209
	v_add_f32_e32 v209, v155, v209
	v_add_f32_e32 v209, v157, v209
	v_exp_f32_e32 v248, v217
	v_add_f32_e32 v209, v152, v209
	v_exp_f32_e32 v249, v218
	v_add_f32_e32 v209, v153, v209
	v_add_f32_e32 v209, v154, v209
	v_exp_f32_e32 v251, v220
	v_add_f32_e32 v209, v156, v209
	v_exp_f32_e32 v217, v221
	v_add_f32_e32 v209, v248, v209
	v_exp_f32_e32 v218, v210
	v_add_f32_e32 v209, v249, v209
	v_add_f32_e32 v209, v250, v209
	v_add_f32_e32 v209, v251, v209
	v_add_f32_e32 v209, v217, v209
	v_add_f32_e32 v209, v218, v209
	v_add_f32_e32 v209, v211, v209
	v_add_f32_e32 v209, v212, v209
	v_add_f32_e32 v209, v213, v209
	v_exp_f32_e32 v220, v222
	v_add_f32_e32 v209, v214, v209
	v_exp_f32_e32 v221, v223
	v_add_f32_e32 v209, v215, v209
	v_add_f32_e32 v209, v216, v209
	v_add_f32_e32 v209, v219, v209
	v_add_f32_e32 v209, v220, v209
	v_add_f32_e32 v209, v221, v209
	v_add_f32_e32 v209, v207, v209
	v_cvt_pk_bf16_f32 v146, v146, v147
	v_cvt_pk_bf16_f32 v147, v148, v159
	v_cvt_pk_bf16_f32 v148, v160, v161
	v_cvt_pk_bf16_f32 v149, v149, v158
	v_cvt_pk_bf16_f32 v150, v150, v151
	v_cvt_pk_bf16_f32 v151, v155, v157
	v_cvt_pk_bf16_f32 v152, v152, v153
	v_cvt_pk_bf16_f32 v153, v154, v156
	v_cvt_pk_bf16_f32 v154, v248, v249
	v_cvt_pk_bf16_f32 v155, v250, v251
	v_cvt_pk_bf16_f32 v156, v217, v218
	v_cvt_pk_bf16_f32 v157, v211, v212
	v_cvt_pk_bf16_f32 v158, v213, v214
	v_cvt_pk_bf16_f32 v159, v215, v216
	v_cvt_pk_bf16_f32 v160, v219, v220
	v_cvt_pk_bf16_f32 v161, v221, v207
	s_waitcnt lgkmcnt(0)
	s_barrier
	s_waitcnt vmcnt(0)
	ds_write_b128 v197, v[130:133]
	ds_write_b128 v198, v[134:137]
	global_load_dwordx2 v[228:229], v179, s[68:69]
	s_add_i32 s98, s82, 2
	s_cmp_gt_u32 s98, s81
	s_cbranch_scc1 .Lp5_a2
	s_add_u32 s98, s16, 0x60000
	s_addc_u32 s99, s17, 0
	global_load_dwordx4 v[130:133], v188, s[98:99]
	s_add_u32 s98, s16, 0x70000
	s_addc_u32 s99, s17, 0
	global_load_dwordx4 v[134:137], v188, s[98:99]
	s_add_u32 s98, s100, 0x60000
	s_addc_u32 s99, s101, 0
	global_load_dwordx4 v[138:141], v188, s[98:99]
	s_add_u32 s98, s100, 0x70000
	s_addc_u32 s99, s101, 0
	global_load_dwordx4 v[142:145], v188, s[98:99]
; template <int KB>
; __device__ __forceinline__ void qkt(f32x16& p0, f32x16& p1, const char* K_lds, int r32, int hi, const bf16x8* qr) {
;     p0 = f32x16{}; p1 = f32x16{};
;     const char* kb[4];
; #pragma unroll
;     for (int dd = 0; dd < 4; ++dd) kb[dd] = K_lds + KB * SHM_K + KSWZ(r32, (dd * 16 + hi * 8) * 2);
; #pragma unroll
;     for (int d0 = 0; d0 < 8; ++d0) { const char* a = kb[d0 & 3] + (d0 >> 2) * 128;
;         bf16x8 b0 = *reinterpret_cast<const bf16x8*>(a);
;         bf16x8 b1 = *reinterpret_cast<const bf16x8*>(a + 32 * 256);
;         p0 = __builtin_amdgcn_mfma_f32_32x32x16_bf16(b0, qr[d0], p0, 0, 0, 0);
;         p1 = __builtin_amdgcn_mfma_f32_32x32x16_bf16(b1, qr[d0], p1, 0, 0, 0); }
; }
; template <int VB>
; __device__ __forceinline__ void pv_tile(f32x16* o, int vb0, bf16x8 pa0, bf16x8 pa1, bf16x8 pa2, bf16x8 pa3) {
;     ...
;     PV_D0(0); PV_D0(1); PV_D0(2); PV_D0(3);
.Lp5_a2:
	ds_read_b128 v[66:69], v199 offset:32768
	ds_read_b128 v[70:73], v199 offset:40960
	ds_read_b128 v[172:175], v200 offset:32768
	ds_read_b128 v[224:227], v200 offset:40960
	ds_read_b128 v[232:235], v201 offset:32768
	ds_read_b128 v[236:239], v201 offset:40960
	ds_read_b128 v[240:243], v202 offset:32768
	ds_read_b128 v[244:247], v202 offset:40960
	s_waitcnt lgkmcnt(7)
	v_mfma_f32_32x32x16_bf16 v[82:97], v[66:69], v[126:129], 0
	s_waitcnt lgkmcnt(6)
	v_mfma_f32_32x32x16_bf16 v[66:81], v[70:73], v[126:129], 0
	s_waitcnt lgkmcnt(5)
	v_mfma_f32_32x32x16_bf16 v[82:97], v[172:175], v[122:125], v[82:97]
	ds_read_b128 v[172:175], v199 offset:32896
	s_waitcnt lgkmcnt(5)
	v_mfma_f32_32x32x16_bf16 v[66:81], v[224:227], v[122:125], v[66:81]
	ds_read_b128 v[224:227], v199 offset:41088
	s_waitcnt lgkmcnt(5)
	v_mfma_f32_32x32x16_bf16 v[82:97], v[232:235], v[118:121], v[82:97]
	ds_read_b128 v[232:235], v200 offset:32896
	s_waitcnt lgkmcnt(5)
	v_mfma_f32_32x32x16_bf16 v[66:81], v[236:239], v[118:121], v[66:81]
	ds_read_b128 v[236:239], v200 offset:41088
	s_waitcnt lgkmcnt(5)
	v_mfma_f32_32x32x16_bf16 v[82:97], v[240:243], v[114:117], v[82:97]
	ds_read_b128 v[240:243], v201 offset:32896
	s_waitcnt lgkmcnt(5)
	v_mfma_f32_32x32x16_bf16 v[66:81], v[244:247], v[114:117], v[66:81]
	ds_read_b128 v[244:247], v201 offset:41088
	s_waitcnt lgkmcnt(5)
	v_mfma_f32_32x32x16_bf16 v[82:97], v[172:175], v[110:113], v[82:97]
	ds_read_b128 v[172:175], v202 offset:32896
	s_waitcnt lgkmcnt(5)
	v_mfma_f32_32x32x16_bf16 v[66:81], v[224:227], v[110:113], v[66:81]
	ds_read_b128 v[224:227], v202 offset:41088
	s_waitcnt lgkmcnt(5)
	v_mfma_f32_32x32x16_bf16 v[82:97], v[232:235], v[106:109], v[82:97]
	s_waitcnt lgkmcnt(4)
	v_mfma_f32_32x32x16_bf16 v[66:81], v[236:239], v[106:109], v[66:81]
	s_waitcnt lgkmcnt(3)
	v_mfma_f32_32x32x16_bf16 v[82:97], v[240:243], v[102:105], v[82:97]
	s_waitcnt lgkmcnt(2)
	v_mfma_f32_32x32x16_bf16 v[66:81], v[244:247], v[102:105], v[66:81]
	s_waitcnt lgkmcnt(1)
	v_mfma_f32_32x32x16_bf16 v[82:97], v[172:175], v[98:101], v[82:97]
	s_waitcnt lgkmcnt(0)
	v_mfma_f32_32x32x16_bf16 v[66:81], v[224:227], v[98:101], v[66:81]
	s_add_i32 s82, s82, 2
	s_cmp_le_u32 s82, s81
	s_cselect_b64 s[36:37], -1, 0
	s_cselect_b32 s76, 1, 0
	s_cmp_gt_u32 s82, s81
	s_cbranch_scc1 .Lp5_skip_ld
.LBB0_1305:
	ds_read_b64_tr_b16 v[212:213], v1 offset:0x4000
	ds_read_b64_tr_b16 v[214:215], v1 offset:0x4800
	ds_read_b64_tr_b16 v[216:217], v1 offset:0x4200
	ds_read_b64_tr_b16 v[218:219], v1 offset:0x4a00
	ds_read_b64_tr_b16 v[220:221], v1 offset:0x4400
	ds_read_b64_tr_b16 v[222:223], v1 offset:0x4c00
	ds_read_b64_tr_b16 v[224:225], v1 offset:0x4600
	ds_read_b64_tr_b16 v[226:227], v1 offset:0x4e00
	ds_read_b64_tr_b16 v[232:233], v1 offset:0x5000
	ds_read_b64_tr_b16 v[234:235], v1 offset:0x5800
	ds_read_b64_tr_b16 v[236:237], v1 offset:0x5200
	ds_read_b64_tr_b16 v[238:239], v1 offset:0x5a00
	ds_read_b64_tr_b16 v[240:241], v1 offset:0x5400
	ds_read_b64_tr_b16 v[242:243], v1 offset:0x5c00
	s_waitcnt lgkmcnt(12)
	v_mfma_f32_32x32x16_bf16 v[2:17], v[146:149], v[212:215], v[2:17]
	ds_read_b64_tr_b16 v[244:245], v1 offset:0x5600
	ds_read_b64_tr_b16 v[246:247], v1 offset:0x5e00
	s_waitcnt lgkmcnt(12)
	v_mfma_f32_32x32x16_bf16 v[50:65], v[146:149], v[216:219], v[50:65]
	ds_read_b64_tr_b16 v[248:249], v1 offset:0x6000
	ds_read_b64_tr_b16 v[250:251], v1 offset:0x6800
	s_waitcnt lgkmcnt(12)
	v_mfma_f32_32x32x16_bf16 v[34:49], v[146:149], v[220:223], v[34:49]
	ds_read_b64_tr_b16 v[220:221], v1 offset:0x6200
	ds_read_b64_tr_b16 v[222:223], v1 offset:0x6a00
	s_waitcnt lgkmcnt(12)
	v_mfma_f32_32x32x16_bf16 v[18:33], v[146:149], v[224:227], v[18:33]
	ds_read_b64_tr_b16 v[224:225], v1 offset:0x6400
	ds_read_b64_tr_b16 v[226:227], v1 offset:0x6c00
	s_waitcnt lgkmcnt(12)
	v_mfma_f32_32x32x16_bf16 v[2:17], v[150:153], v[232:235], v[2:17]
	ds_read_b64_tr_b16 v[232:233], v1 offset:0x6600
	ds_read_b64_tr_b16 v[234:235], v1 offset:0x6e00
	s_waitcnt lgkmcnt(12)
	v_mfma_f32_32x32x16_bf16 v[50:65], v[150:153], v[236:239], v[50:65]
	ds_read_b64_tr_b16 v[236:237], v1 offset:0x7000
	ds_read_b64_tr_b16 v[238:239], v1 offset:0x7800
	s_waitcnt lgkmcnt(12)
	v_mfma_f32_32x32x16_bf16 v[34:49], v[150:153], v[240:243], v[34:49]
	ds_read_b64_tr_b16 v[240:241], v1 offset:0x7200
	ds_read_b64_tr_b16 v[242:243], v1 offset:0x7a00
	s_waitcnt lgkmcnt(12)
	v_mfma_f32_32x32x16_bf16 v[18:33], v[150:153], v[244:247], v[18:33]
	ds_read_b64_tr_b16 v[244:245], v1 offset:0x7400
	ds_read_b64_tr_b16 v[246:247], v1 offset:0x7c00
	s_waitcnt lgkmcnt(12)
	v_mfma_f32_32x32x16_bf16 v[2:17], v[154:157], v[248:251], v[2:17]
	ds_read_b64_tr_b16 v[248:249], v1 offset:0x7600
	ds_read_b64_tr_b16 v[250:251], v1 offset:0x7e00
	s_waitcnt lgkmcnt(12)
	v_mfma_f32_32x32x16_bf16 v[50:65], v[154:157], v[220:223], v[50:65]
	s_waitcnt lgkmcnt(10)
	v_mfma_f32_32x32x16_bf16 v[34:49], v[154:157], v[224:227], v[34:49]
	s_waitcnt lgkmcnt(8)
	v_mfma_f32_32x32x16_bf16 v[18:33], v[154:157], v[232:235], v[18:33]
	s_waitcnt lgkmcnt(6)
	v_mfma_f32_32x32x16_bf16 v[2:17], v[158:161], v[236:239], v[2:17]
	s_waitcnt lgkmcnt(4)
	v_mfma_f32_32x32x16_bf16 v[50:65], v[158:161], v[240:243], v[50:65]
	s_waitcnt lgkmcnt(2)
	v_mfma_f32_32x32x16_bf16 v[34:49], v[158:161], v[244:247], v[34:49]
	s_waitcnt lgkmcnt(0)
	v_mfma_f32_32x32x16_bf16 v[18:33], v[158:161], v[248:251], v[18:33]
	s_cmp_eq_u64 s[36:37], 0
	s_cbranch_scc1 .Lp5_kw2_skip
	s_waitcnt vmcnt(0)
	ds_write_b128 v204, v[138:141] offset:49152
	ds_write_b128 v204, v[142:145] offset:57344
; __device__ __forceinline__ void sel_mask_tile(f32x16& p0, f32x16& p1, unsigned wlo, unsigned whi, int hi) {
;     const unsigned NEGB = 0xff800000u;
;     const unsigned lo = wlo >> (4 * hi), h2 = whi >> (4 * hi);
; #pragma unroll
;     for (int r = 0; r < 16; ++r) {
;         const int c = (r & 3) + 8 * (r >> 2);
;         const unsigned m0 = (unsigned)__builtin_amdgcn_sbfe((int)lo, c, 1), m1 = (unsigned)__builtin_amdgcn_sbfe((int)h2, c, 1);
;         p0[r] = __uint_as_float((__float_as_uint(p0[r]) & m0) | (NEGB & ~m0));
;         p1[r] = __uint_as_float((__float_as_uint(p1[r]) & m1) | (NEGB & ~m1));
;     }
; }
; __device__ __forceinline__ void partialSM(f32x16& p0, f32x16& p1, float& m_reg, float& mn, float& alpha) {
;     float pmax = p0[0];
; #pragma unroll
;     for (int r = 1; r < 16; ++r) pmax = fmaxf(pmax, p0[r]);
; #pragma unroll
;     for (int r = 0; r < 16; ++r) pmax = fmaxf(pmax, p1[r]);
;     { auto rr = __builtin_amdgcn_permlane32_swap(__float_as_uint(pmax), __float_as_uint(pmax), false, false);
;       pmax = fmaxf(__uint_as_float(rr[0]), __uint_as_float(rr[1])); }
;     constexpr float C2 = 1.4426950408889634f * SCALE;
;     if (__builtin_expect(__all((pmax - m_reg) * SCALE <= THR), 1)) { mn = m_reg; alpha = 1.f; }
;     else { mn = fmaxf(m_reg, pmax); alpha = __builtin_amdgcn_exp2f((m_reg - mn) * C2); m_reg = mn; }
.Lp5_kw2_skip:
	s_waitcnt lgkmcnt(0)
	s_barrier
	s_nop 0
	s_waitcnt vmcnt(4)
	v_lshrrev_b32_e32 v193, v163, v228
	v_bfe_i32 v192, v193, 0, 1
	v_bitop3_b32 v192, v82, s74, v192 bitop3:0xe4
	v_bfe_i32 v82, v193, 1, 1
	v_bitop3_b32 v146, v83, s74, v82 bitop3:0xe4
	v_bfe_i32 v82, v193, 2, 1
	v_bitop3_b32 v147, v84, s74, v82 bitop3:0xe4
	v_bfe_i32 v82, v193, 3, 1
	v_bitop3_b32 v148, v85, s74, v82 bitop3:0xe4
	v_bfe_i32 v82, v193, 8, 1
	v_bitop3_b32 v149, v86, s74, v82 bitop3:0xe4
	v_bfe_i32 v82, v193, 9, 1
	v_bitop3_b32 v150, v87, s74, v82 bitop3:0xe4
	v_bfe_i32 v82, v193, 10, 1
	v_bitop3_b32 v88, v88, s74, v82 bitop3:0xe4
	v_bfe_i32 v82, v193, 11, 1
	v_bitop3_b32 v89, v89, s74, v82 bitop3:0xe4
	v_bfe_i32 v82, v193, 16, 1
	v_bitop3_b32 v90, v90, s74, v82 bitop3:0xe4
	v_bfe_i32 v82, v193, 17, 1
	v_bitop3_b32 v91, v91, s74, v82 bitop3:0xe4
	v_bfe_i32 v82, v193, 18, 1
	v_bitop3_b32 v92, v92, s74, v82 bitop3:0xe4
	v_bfe_i32 v82, v193, 19, 1
	v_bitop3_b32 v93, v93, s74, v82 bitop3:0xe4
	v_bfe_i32 v82, v193, 24, 1
	v_bitop3_b32 v94, v94, s74, v82 bitop3:0xe4
	v_bfe_i32 v82, v193, 25, 1
	v_bitop3_b32 v95, v95, s74, v82 bitop3:0xe4
	v_bfe_i32 v82, v193, 26, 1
	v_bitop3_b32 v96, v96, s74, v82 bitop3:0xe4
	v_bfe_i32 v82, v193, 27, 1
	v_bitop3_b32 v97, v97, s74, v82 bitop3:0xe4
	v_max_f32_e32 v82, v192, v146
	v_max3_f32 v82, v82, v147, v148
	v_max3_f32 v82, v82, v149, v150
	v_max3_f32 v82, v82, v88, v89
	v_max3_f32 v82, v82, v90, v91
	v_lshrrev_b32_e32 v194, v163, v229
	v_max3_f32 v82, v82, v92, v93
	v_bfe_i32 v195, v194, 0, 1
	v_bfe_i32 v172, v194, 1, 1
	v_max3_f32 v82, v82, v94, v95
	v_bitop3_b32 v66, v66, s74, v195 bitop3:0xe4
	v_bfe_i32 v83, v194, 2, 1
	v_bfe_i32 v84, v194, 3, 1
	v_max3_f32 v230, v82, v96, v97
	v_bitop3_b32 v67, v67, s74, v172 bitop3:0xe4
	v_bfe_i32 v85, v194, 8, 1
	v_bfe_i32 v86, v194, 9, 1
	v_bitop3_b32 v82, v68, s74, v83 bitop3:0xe4
	v_max3_f32 v68, v230, v66, v67
	v_bitop3_b32 v83, v69, s74, v84 bitop3:0xe4
	v_bfe_i32 v87, v194, 10, 1
	v_bfe_i32 v151, v194, 11, 1
	v_bitop3_b32 v84, v70, s74, v85 bitop3:0xe4
	v_max3_f32 v68, v68, v82, v83
	v_bitop3_b32 v85, v71, s74, v86 bitop3:0xe4
	v_bfe_i32 v152, v194, 16, 1
	v_bfe_i32 v153, v194, 17, 1
	v_bitop3_b32 v86, v72, s74, v87 bitop3:0xe4
	v_max3_f32 v68, v68, v84, v85
	v_bitop3_b32 v87, v73, s74, v151 bitop3:0xe4
	v_bfe_i32 v154, v194, 18, 1
	v_bfe_i32 v155, v194, 19, 1
	v_bitop3_b32 v74, v74, s74, v152 bitop3:0xe4
	v_max3_f32 v69, v68, v86, v87
	v_bitop3_b32 v75, v75, s74, v153 bitop3:0xe4
	v_bfe_i32 v156, v194, 24, 1
	v_bfe_i32 v157, v194, 25, 1
	v_bitop3_b32 v68, v76, s74, v154 bitop3:0xe4
	v_max3_f32 v71, v69, v74, v75
	v_bitop3_b32 v69, v77, s74, v155 bitop3:0xe4
	v_bfe_i32 v230, v194, 26, 1
	v_bfe_i32 v231, v194, 27, 1
	v_bitop3_b32 v70, v78, s74, v156 bitop3:0xe4
	v_max3_f32 v73, v71, v68, v69
	v_bitop3_b32 v71, v79, s74, v157 bitop3:0xe4
	v_bitop3_b32 v72, v80, s74, v230 bitop3:0xe4
	v_max3_f32 v76, v73, v70, v71
	v_bitop3_b32 v73, v81, s74, v231 bitop3:0xe4
	v_max3_f32 v76, v76, v72, v73
	v_mov_b32_e32 v77, v76
	s_nop 1
	v_permlane32_swap_b32_e32 v76, v77
	v_max_f32_e32 v76, v76, v77
	v_sub_f32_e32 v77, v76, v206
	v_mul_f32_e32 v77, 0x3db504f3, v77
	v_cmp_ge_f32_e32 vcc, s75, v77
	s_cmp_eq_u64 vcc, exec
	s_cselect_b64 s[6:7], -1, 0
.LBB0_1307:
	v_mov_b32_e32 v207, 1.0
	s_not_b64 vcc, s[6:7]
	s_cbranch_vccz .LBB0_1311
	v_max_f32_e32 v76, v206, v76
	v_sub_f32_e32 v77, v206, v76
	v_mul_f32_e32 v77, 0x3e0293ee, v77
	v_exp_f32_e32 v77, v77
	s_nop 0
	v_cndmask_b32_e64 v207, v77, 1.0, s[6:7]

	s_and_saveexec_b64 s[36:37], s[0:1]

	ds_write_b32 v185, v207 offset:128

	s_or_b64 exec, exec, s[36:37]

	s_waitcnt lgkmcnt(0)

; __device__ __forceinline__ void partialSM(f32x16& p0, f32x16& p1, float& m_reg, float& mn, float& alpha) {
;     ...
;     else { mn = fmaxf(m_reg, pmax); alpha = __builtin_amdgcn_exp2f((m_reg - mn) * C2); m_reg = mn; }
;     const float mnL = -mn * C2;
; #pragma unroll
;     for (int r = 0; r < 16; ++r) p0[r] = fmaf(p0[r], C2, mnL);
; #pragma unroll
;     for (int r = 0; r < 16; ++r) p1[r] = fmaf(p1[r], C2, mnL);
; #pragma unroll
;     for (int r = 0; r < 16; ++r) p0[r] = __builtin_amdgcn_exp2f(p0[r]);
	ds_read_b128 v[78:81], v183 offset:224
	ds_read_b128 v[240:243], v183 offset:192
	ds_read_b128 v[244:247], v183 offset:160
	ds_read_b128 v[248:251], v183 offset:128
	s_waitcnt lgkmcnt(3)
	v_pk_mul_f32 v[16:17], v[16:17], v[80:81]
	s_waitcnt lgkmcnt(2)
	v_pk_mul_f32 v[12:13], v[12:13], v[242:243]
	s_waitcnt lgkmcnt(1)
	v_pk_mul_f32 v[8:9], v[8:9], v[246:247]
	s_waitcnt lgkmcnt(0)
	v_pk_mul_f32 v[4:5], v[4:5], v[250:251]
	v_pk_mul_f32 v[14:15], v[14:15], v[78:79]
	v_pk_mul_f32 v[10:11], v[10:11], v[240:241]
	v_pk_mul_f32 v[6:7], v[6:7], v[244:245]
	v_pk_mul_f32 v[2:3], v[2:3], v[248:249]
	v_pk_mul_f32 v[64:65], v[64:65], v[80:81]
	v_pk_mul_f32 v[60:61], v[60:61], v[242:243]
	v_pk_mul_f32 v[56:57], v[56:57], v[246:247]
	v_pk_mul_f32 v[52:53], v[52:53], v[250:251]
	v_pk_mul_f32 v[62:63], v[62:63], v[78:79]
	v_pk_mul_f32 v[58:59], v[58:59], v[240:241]
	v_pk_mul_f32 v[54:55], v[54:55], v[244:245]
	v_pk_mul_f32 v[50:51], v[50:51], v[248:249]
	v_pk_mul_f32 v[48:49], v[48:49], v[80:81]
	v_pk_mul_f32 v[44:45], v[44:45], v[242:243]
	v_pk_mul_f32 v[40:41], v[40:41], v[246:247]
	v_pk_mul_f32 v[36:37], v[36:37], v[250:251]
	v_pk_mul_f32 v[46:47], v[46:47], v[78:79]
	v_pk_mul_f32 v[42:43], v[42:43], v[240:241]
	v_pk_mul_f32 v[38:39], v[38:39], v[244:245]
	v_pk_mul_f32 v[34:35], v[34:35], v[248:249]
	v_pk_mul_f32 v[32:33], v[32:33], v[80:81]
	v_pk_mul_f32 v[28:29], v[28:29], v[242:243]
	v_pk_mul_f32 v[24:25], v[24:25], v[246:247]
	v_pk_mul_f32 v[20:21], v[20:21], v[250:251]
	v_pk_mul_f32 v[30:31], v[30:31], v[78:79]
	v_pk_mul_f32 v[26:27], v[26:27], v[240:241]
	v_pk_mul_f32 v[22:23], v[22:23], v[244:245]
	v_pk_mul_f32 v[18:19], v[18:19], v[248:249]
.LBB0_1311:
	v_cndmask_b32_e64 v206, v76, v206, s[6:7]
	v_mul_f32_e32 v76, 0xbe0293ee, v206
	v_mov_b32_e32 v251, v76
	v_fmamk_f32 v77, v192, 0x3e0293ee, v76
	v_fmamk_f32 v78, v146, 0x3e0293ee, v76
	v_fmamk_f32 v79, v147, 0x3e0293ee, v76
	v_fmamk_f32 v80, v148, 0x3e0293ee, v76
	v_fmamk_f32 v81, v149, 0x3e0293ee, v76
	v_fmamk_f32 v250, v150, 0x3e0293ee, v76
	v_fmamk_f32 v88, v88, 0x3e0293ee, v76
	v_fmamk_f32 v89, v89, 0x3e0293ee, v76
	v_fmamk_f32 v90, v90, 0x3e0293ee, v76
	v_fmamk_f32 v91, v91, 0x3e0293ee, v76
	v_fmamk_f32 v92, v92, 0x3e0293ee, v76
	v_fmamk_f32 v93, v93, 0x3e0293ee, v76
	v_fmamk_f32 v94, v94, 0x3e0293ee, v76
	v_fmamk_f32 v95, v95, 0x3e0293ee, v76
	v_fmamk_f32 v96, v96, 0x3e0293ee, v76
	v_fmac_f32_e32 v251, 0x3e0293ee, v97
	v_exp_f32_e32 v219, v77
	v_exp_f32_e32 v220, v78
	v_exp_f32_e32 v221, v79
	v_exp_f32_e32 v222, v80
	v_exp_f32_e32 v223, v81
	v_exp_f32_e32 v225, v250
	v_exp_f32_e32 v224, v88
	v_exp_f32_e32 v226, v89
	v_exp_f32_e32 v211, v90
	v_exp_f32_e32 v212, v91
	v_exp_f32_e32 v213, v92
	v_exp_f32_e32 v215, v93
	v_exp_f32_e32 v214, v94
	v_exp_f32_e32 v216, v95
	v_exp_f32_e32 v217, v96
	v_exp_f32_e32 v218, v251
	v_pk_fma_f32 v[194:195], v[66:67], s[14:15], v[76:77] op_sel_hi:[1,0,0]
	v_fmac_f32_e32 v181, v177, v205
	v_pk_fma_f32 v[192:193], v[82:83], s[14:15], v[76:77] op_sel_hi:[1,0,0]
	v_pk_fma_f32 v[158:159], v[84:85], s[14:15], v[76:77] op_sel_hi:[1,0,0]
	v_pk_fma_f32 v[154:155], v[86:87], s[14:15], v[76:77] op_sel_hi:[1,0,0]
	v_pk_fma_f32 v[150:151], v[74:75], s[14:15], v[76:77] op_sel_hi:[1,0,0]
	v_pk_fma_f32 v[160:161], v[68:69], s[14:15], v[76:77] op_sel_hi:[1,0,0]
	v_pk_fma_f32 v[156:157], v[70:71], s[14:15], v[76:77] op_sel_hi:[1,0,0]
	v_pk_fma_f32 v[152:153], v[72:73], s[14:15], v[76:77] op_sel_hi:[1,0,0]
	v_fma_f32 v205, v181, v208, v209
	v_add_u32_e32 v179, 16, v179
	s_add_u32 s16, s16, 0x40000
	s_addc_u32 s17, s17, 0
	s_add_u32 s100, s100, 0x40000
	s_addc_u32 s101, s101, 0
	s_cmp_ge_u32 s82, s81
	s_cbranch_scc1 .Lp5_exit
	v_mov_b32_e32 v177, v207
	s_branch .LBB0_1299

; __device__ __forceinline__ void attn_block(const BlockRef& cur, const BlockRef& nxt, char* lds, Seam& S) {
;     ...
;     for (int t = 1; t + 1 < NT; t += 2) {
;         HALF_STEP(pB0, pB1, mnB, alB, pA0, pA1, alA, t, 1, 0, 0);
;         HALF_STEP(pA0, pA1, mnA, alA, pB0, pB1, alB, t + 1, 0, 1, 1);
;     }
;     mw = LDMASK(NT - 1);
.Lp5_exit:
	s_cmp_lg_u32 s77, 0
	s_cbranch_scc1 .Lp5_exit_b
	s_waitcnt lgkmcnt(0)
	s_barrier
.Lp5_exit_b:
	s_cmp_eq_u32 s76, 0
	s_cbranch_scc1 .Lp5_vw_x
	s_waitcnt vmcnt(0)
	ds_write_b128 v197, v[130:133] offset:16384
	ds_write_b128 v198, v[134:137] offset:16384
